# P0 transposer: last iteration skips the pacing sleep and the dummy re-load of its own item (16 MB less traffic before the x->U phase); on top of v068
# baseline (speedup 1.0000x reference)
; __device__ __forceinline__ void p0_prologue(const Ptrs& P, LAS unsigned char* lds, int vcu, int G, int tid) {
;     ...
;         for (int it = gw; it < NITEMS; it += NGW) {
;             const int nit = it + NGW; const bool has_n = nit < NITEMS;
;             f32x4 nv[8];
;             const TItem nxt = t_decode(P, has_n ? nit : it, lane); t_load(nxt, nv);
.LBB0_39:
	s_cmp_eq_u32 s50, s3
	s_cbranch_scc1 .Lp0_nosleep
	s_add_i32 s94, s50, s0
	s_cmp_gt_i32 s94, 0xffff
	s_cbranch_scc1 .Lp0_nosleep
	s_sleep 80

; #define LAS __attribute__((address_space(3)))
; __device__ __forceinline__ void t_load(const TItem& t, f32x4 (&v)[8]) {
; #pragma unroll
;     for (int j = 0; j < 8; ++j) v[j] = __builtin_nontemporal_load((const f32x4*)(t.src + (size_t)(8 * j) * t.N));
; }
; __device__ __forceinline__ void p0_prologue(const Ptrs& P, LAS unsigned char* lds, int vcu, int G, int tid) {
;     const int lane = tid & 63, wave = __builtin_amdgcn_readfirstlane(tid >> 6);
;     LAS float* scr = (LAS float*)(lds + wave * 16384);
;     const int gw = vcu * 8 + wave, NGW = G * 8;
;     constexpr int NITEMS = (D / 64) * (NIN / 32) + 2 * (HW / 64) * (D / 32) + (D / 64) * (D / 32);
;     if (gw < NITEMS) {
;         TItem cur = t_decode(P, gw, lane); f32x4 v[8]; t_load(cur, v);
;         for (int it = gw; it < NITEMS; it += NGW) {
;             const int nit = it + NGW; const bool has_n = nit < NITEMS;
;             f32x4 nv[8];
;             const TItem nxt = t_decode(P, has_n ? nit : it, lane); t_load(nxt, nv);
;             const int c4 = 4 * (lane & 7), r8 = lane >> 3;
; #pragma unroll
;             for (int j = 0; j < 8; ++j) { LAS float* d = scr + (8 * j + r8) * 33 + c4; d[0] = v[j][0]; d[1] = v[j][1]; d[2] = v[j][2]; d[3] = v[j][3]; }
;             asm volatile("s_waitcnt lgkmcnt(0)" ::: "memory");
;             const int c = lane & 7;
;             if (cur.f8) {
; #pragma unroll
;                 for (int j = 0; j < 4; ++j) { const int n = (lane >> 3) + 8 * j; const LAS float* sp = scr + (8 * c) * 33 + n;
;                     int w0 = 0, w1 = 0;
;                     w0 = __builtin_amdgcn_cvt_pk_fp8_f32(sp[0 * 33] * F8_SW, sp[1 * 33] * F8_SW, w0, false); w0 = __builtin_amdgcn_cvt_pk_fp8_f32(sp[2 * 33] * F8_SW, sp[3 * 33] * F8_SW, w0, true);
;                     w1 = __builtin_amdgcn_cvt_pk_fp8_f32(sp[4 * 33] * F8_SW, sp[5 * 33] * F8_SW, w1, false); w1 = __builtin_amdgcn_cvt_pk_fp8_f32(sp[6 * 33] * F8_SW, sp[7 * 33] * F8_SW, w1, true);
;                     u32x2 o; o.x = (unsigned)w0; o.y = (unsigned)w1;
;                     *(u32x2*)((unsigned char*)cur.dst + (size_t)n * cur.ldk + 8 * c) = o; }
.LBB0_62:
	s_lshl_b32 s20, s26, 5
	v_lshl_add_u64 v[42:43], v[78:79], 0, s[20:21]
	v_lshl_add_u64 v[44:45], v[42:43], 0, s[20:21]
	v_lshl_add_u64 v[50:51], v[44:45], 0, s[20:21]
	v_lshl_add_u64 v[52:53], v[50:51], 0, s[20:21]
	v_lshl_add_u64 v[58:59], v[52:53], 0, s[20:21]
	v_lshl_add_u64 v[60:61], v[58:59], 0, s[20:21]
	s_and_b64 vcc, exec, s[22:23]
	s_cbranch_vccnz .Lp0_skipld
	global_load_dwordx4 v[34:37], v[42:43], off nt
	global_load_dwordx4 v[38:41], v[44:45], off nt
	s_nop 0
	global_load_dwordx4 v[42:45], v[50:51], off nt
	global_load_dwordx4 v[46:49], v[52:53], off nt
	s_nop 0
	global_load_dwordx4 v[50:53], v[58:59], off nt
	global_load_dwordx4 v[54:57], v[60:61], off nt
	v_lshl_add_u64 v[86:87], v[60:61], 0, s[20:21]
	global_load_dwordx4 v[62:65], v[78:79], off nt
	global_load_dwordx4 v[58:61], v[86:87], off nt
.Lp0_skipld:
	s_waitcnt vmcnt(12)
	ds_write2_b32 v85, v30, v31 offset1:1
	ds_write2_b32 v85, v32, v33 offset0:2 offset1:3
	v_add_u32_e32 v30, 0x420, v85
	ds_write2_b32 v30, v26, v27 offset1:1
	v_add_u32_e32 v26, 0x428, v85
	ds_write2_b32 v26, v28, v29 offset1:1
	v_add_u32_e32 v26, 0x840, v85
	ds_write2_b32 v26, v22, v23 offset1:1
	v_add_u32_e32 v22, 0x848, v85
	ds_write2_b32 v22, v24, v25 offset1:1
	v_add_u32_e32 v22, 0xc60, v85
	ds_write2_b32 v22, v18, v19 offset1:1
	v_add_u32_e32 v18, 0xc68, v85
	ds_write2_b32 v18, v20, v21 offset1:1
	v_add_u32_e32 v18, 0x1080, v85
	ds_write2_b32 v18, v14, v15 offset1:1
	v_add_u32_e32 v14, 0x1088, v85
	ds_write2_b32 v14, v16, v17 offset1:1
	v_add_u32_e32 v14, 0x14a0, v85
	ds_write2_b32 v14, v10, v11 offset1:1
	v_add_u32_e32 v10, 0x14a8, v85
	ds_write2_b32 v10, v12, v13 offset1:1
	v_add_u32_e32 v10, 0x18c0, v85
	ds_write2_b32 v10, v6, v7 offset1:1
	v_add_u32_e32 v6, 0x18c8, v85
	ds_write2_b32 v6, v8, v9 offset1:1
	v_add_u32_e32 v6, 0x1ce0, v85
	ds_write2_b32 v6, v2, v3 offset1:1
	v_add_u32_e32 v2, 0x1ce8, v85
	ds_write2_b32 v2, v4, v5 offset1:1
	s_waitcnt lgkmcnt(0)
	ds_read_b32 v2, v84
	s_cmp_eq_u32 s51, 0
	s_cbranch_scc1 .LBB0_64
	ds_read2_b32 v[4:5], v84 offset0:24 offset1:33
	ds_read2_b32 v[10:11], v84 offset0:57 offset1:66
	ds_read2_b32 v[12:13], v84 offset0:90 offset1:99
	s_waitcnt lgkmcnt(3)
	v_mul_f32_e32 v3, 0x43800000, v2
	v_mov_b32_e32 v8, v69
	s_waitcnt lgkmcnt(2)
	v_mul_f32_e32 v5, 0x43800000, v5
	ds_read2_b32 v[14:15], v84 offset0:123 offset1:132
	ds_read2_b32 v[16:17], v84 offset0:156 offset1:165
	v_cvt_pk_fp8_f32 v8, v3, v5
	s_waitcnt lgkmcnt(3)
	v_mul_f32_e32 v3, 0x43800000, v11
	s_waitcnt lgkmcnt(2)
	v_mul_f32_e32 v5, 0x43800000, v13
	ds_read2_b32 v[18:19], v84 offset0:189 offset1:198
	ds_read2_b32 v[20:21], v84 offset0:222 offset1:231
	v_cvt_pk_fp8_f32 v8, v3, v5 op_sel:[0,0,1]
	s_waitcnt lgkmcnt(3)
	v_mul_f32_e32 v3, 0x43800000, v15
	s_waitcnt lgkmcnt(2)
	v_mul_f32_e32 v5, 0x43800000, v17
	v_mov_b32_e32 v9, v69
	ds_read2_b32 v[22:23], v84 offset0:8 offset1:16
	ds_read2_b32 v[24:25], v84 offset0:41 offset1:49
	v_cvt_pk_fp8_f32 v9, v3, v5
	ds_read2_b32 v[28:29], v84 offset0:74 offset1:82
	ds_read2_b32 v[30:31], v84 offset0:107 offset1:115
	ds_read2_b32 v[32:33], v84 offset0:140 offset1:148
	ds_read2_b32 v[78:79], v84 offset0:173 offset1:181
	s_waitcnt lgkmcnt(7)
	v_mul_f32_e32 v3, 0x43800000, v19
	s_waitcnt lgkmcnt(6)
	v_mul_f32_e32 v5, 0x43800000, v21
	v_cvt_pk_fp8_f32 v9, v3, v5 op_sel:[0,0,1]
	s_waitcnt lgkmcnt(5)
	v_mul_f32_e32 v3, 0x43800000, v22
	s_waitcnt lgkmcnt(4)
	v_mul_f32_e32 v5, 0x43800000, v24
	v_mov_b32_e32 v26, v69
	ds_read2_b32 v[86:87], v84 offset0:206 offset1:214
	ds_read2_b32 v[88:89], v84 offset0:239 offset1:247
	v_cvt_pk_fp8_f32 v26, v3, v5
	s_waitcnt lgkmcnt(3)
	v_mul_f32_e32 v11, 0x43800000, v32
	s_waitcnt lgkmcnt(2)
	v_mul_f32_e32 v13, 0x43800000, v78
	v_mov_b32_e32 v27, v69
	v_cvt_pk_fp8_f32 v27, v11, v13
	v_mul_f32_e32 v3, 0x43800000, v28
	v_mul_f32_e32 v5, 0x43800000, v30
	v_cvt_pk_fp8_f32 v26, v3, v5 op_sel:[0,0,1]
	s_waitcnt lgkmcnt(1)
	v_mul_f32_e32 v3, 0x43800000, v86
	s_waitcnt lgkmcnt(0)
	v_mul_f32_e32 v5, 0x43800000, v88
	v_cvt_pk_fp8_f32 v27, v3, v5 op_sel:[0,0,1]
	v_lshl_add_u64 v[6:7], s[18:19], 0, v[66:67]
	v_lshl_add_u64 v[92:93], v[6:7], 0, v[70:71]
	global_store_dwordx2 v[92:93], v[8:9], off sc1
	v_lshl_add_u64 v[8:9], v[6:7], 0, v[72:73]
	global_store_dwordx2 v[8:9], v[26:27], off sc1
	v_mul_f32_e32 v3, 0x43800000, v23
	v_mul_f32_e32 v5, 0x43800000, v25
	v_mov_b32_e32 v8, v69
	v_cvt_pk_fp8_f32 v8, v3, v5
	v_mul_f32_e32 v11, 0x43800000, v33
	v_mul_f32_e32 v13, 0x43800000, v79
	v_mov_b32_e32 v9, v69
	v_cvt_pk_fp8_f32 v9, v11, v13
	v_mul_f32_e32 v3, 0x43800000, v29
	v_mul_f32_e32 v5, 0x43800000, v31
	v_cvt_pk_fp8_f32 v8, v3, v5 op_sel:[0,0,1]
	v_mul_f32_e32 v3, 0x43800000, v87
	v_mul_f32_e32 v5, 0x43800000, v89
	v_cvt_pk_fp8_f32 v9, v3, v5 op_sel:[0,0,1]
	v_mul_f32_e32 v3, 0x43800000, v4
	v_mul_f32_e32 v5, 0x43800000, v10
	v_mov_b32_e32 v4, v69
	ds_read_b32 v13, v84 offset:1020
	v_cvt_pk_fp8_f32 v4, v3, v5
	v_mul_f32_e32 v3, 0x43800000, v12
	v_mul_f32_e32 v11, 0x43800000, v16
	v_mul_f32_e32 v12, 0x43800000, v18
	v_mov_b32_e32 v5, v69
	v_cvt_pk_fp8_f32 v5, v11, v12
	v_mul_f32_e32 v10, 0x43800000, v14
	v_cvt_pk_fp8_f32 v4, v3, v10 op_sel:[0,0,1]
	v_mul_f32_e32 v3, 0x43800000, v20
	s_waitcnt lgkmcnt(0)
	v_mul_f32_e32 v10, 0x43800000, v13
	v_cvt_pk_fp8_f32 v5, v3, v10 op_sel:[0,0,1]
	v_lshl_add_u64 v[10:11], v[6:7], 0, v[74:75]
	v_lshl_add_u64 v[6:7], v[6:7], 0, v[76:77]
	global_store_dwordx2 v[10:11], v[8:9], off sc1
	global_store_dwordx2 v[6:7], v[4:5], off sc1
	s_cbranch_execnz .LBB0_38
	s_branch .LBB0_37
